# LRU: barrier between gate block and pass 1 dropped, carry-in pairs read up front; attention QK: K fragments of all key tiles read ahead with counted waits
# baseline (speedup 1.0000x reference)
; #define LAS __attribute__((address_space(3)))
; __device__ __forceinline__ float sigmoidf_(float x) { return __builtin_amdgcn_rcpf(1.f + __expf(-x)); }
; __device__ __forceinline__ void lru_chain(unsigned char* ws_, const float* const* in_, int l_, LAS unsigned char* lds, int tid, int bid, int G) {
;     ...
;             { const int tok = 16 * w + j; bf16x8 bfr[2];
; #pragma unroll
;               for (int c = 0; c < 2; ++c) bfr[c] = *(const LAS bf16x8*)(UB + tok * 144 + kq * 16 + c * 64);
; #pragma unroll
;               for (int ot = 0; ot < 4; ++ot) { f32x4 da = (f32x4){0.f, 0.f, 0.f, 0.f}, dx = da;
; #pragma unroll
;                   for (int c = 0; c < 2; ++c) { const bf16x8 fa = *(const LAS bf16x8*)(WT + (16 * ot + j) * 144 + kq * 16 + c * 64), fx = *(const LAS bf16x8*)(WT + (64 + 16 * ot + j) * 144 + kq * 16 + c * 64);
;                       da = __builtin_amdgcn_mfma_f32_16x16x32_bf16(fa, bfr[c], da, 0, 0, 0); dx = __builtin_amdgcn_mfma_f32_16x16x32_bf16(fx, bfr[c], dx, 0, 0, 0); }
;                   const int ch = 16 * ot + 4 * kq;
;                   const f32x4 ba4 = *(const LAS f32x4*)(PRM + ch), bx4 = *(const LAS f32x4*)(PRM + 64 + ch), sp4 = *(const LAS f32x4*)(PRM + 128 + ch);
;                   const f32x4 u4 = *(const LAS f32x4*)(B_ + tok * 68 + ch); f32x4 a4, b4;
; #pragma unroll
;                   for (int e = 0; e < 4; ++e) { const float rg = sigmoidf_(da[e] + ba4[e]), ig = sigmoidf_(dx[e] + bx4[e]); const float la = -8.0f * rg * sp4[e];
;                       const float av_ = __expf(la); a4[e] = av_; b4[e] = sqrtf(fmaxf(1.0f - av_ * av_, 0.f)) * ig * u4[e]; }
;                   *(LAS f32x4*)(A_ + tok * 68 + ch) = a4; *(LAS f32x4*)(B_ + tok * 68 + ch) = b4; } }
.LBB0_201:
	v_add_u32_e32 v1, v160, v161
	ds_read_b128 v[76:79], v1
	ds_read_b128 v[72:75], v1 offset:64
	s_lshl_b32 s2, s85, 6
	s_and_b32 s2, s2, 64
	s_mov_b32 s3, s80
	s_mov_b32 s6, 0xbfb8aa3b
	s_mov_b32 s10, 0x3fb8aa3b
	s_mov_b32 s98, 0xc1000000
	s_mov_b32 s100, 1.0
	v_mov_b32_e32 v2, 0x4f800000
	v_mov_b32_e32 v3, 0x37800000
	ds_read_b128 v[236:239], v203 offset:0
	ds_read_b128 v[244:247], v203 offset:9216
	ds_read_b128 v[180:183], v203 offset:64
	ds_read_b128 v[240:243], v203 offset:9280
	ds_read_b128 v[96:99], v166
	ds_read_b128 v[208:211], v167
	ds_read_b128 v[216:219], v168
	ds_read_b128 v[224:227], v169 offset:53248
	ds_read_b128 v[100:103], v170
	ds_read_b128 v[212:215], v171
	ds_read_b128 v[220:223], v172
	ds_read_b128 v[228:231], v169 offset:53312
	s_waitcnt lgkmcnt(11)
	v_mfma_f32_16x16x32_bf16 v[80:83], v[236:239], v[76:79], 0
	s_waitcnt lgkmcnt(10)
	v_mfma_f32_16x16x32_bf16 v[88:91], v[244:247], v[76:79], 0
	s_waitcnt lgkmcnt(9)
	v_mfma_f32_16x16x32_bf16 v[80:83], v[180:183], v[72:75], v[80:83]
	s_waitcnt lgkmcnt(8)
	v_mfma_f32_16x16x32_bf16 v[88:91], v[240:243], v[72:75], v[88:91]
	ds_read_b128 v[236:239], v203 offset:2304
	ds_read_b128 v[244:247], v203 offset:11520
	ds_read_b128 v[180:183], v203 offset:2368
	ds_read_b128 v[240:243], v203 offset:11584
	s_waitcnt lgkmcnt(3)
	v_mfma_f32_16x16x32_bf16 v[84:87], v[236:239], v[76:79], 0
	s_waitcnt lgkmcnt(2)
	v_mfma_f32_16x16x32_bf16 v[92:95], v[244:247], v[76:79], 0
	s_waitcnt lgkmcnt(1)
	v_mfma_f32_16x16x32_bf16 v[84:87], v[180:183], v[72:75], v[84:87]
	s_waitcnt lgkmcnt(0)
	v_mfma_f32_16x16x32_bf16 v[92:95], v[240:243], v[72:75], v[92:95]
	s_waitcnt lgkmcnt(0)
	s_nop 7
	v_pk_add_f32 v[80:81], v[80:81], v[96:97]
	v_pk_add_f32 v[82:83], v[82:83], v[98:99]
	v_pk_add_f32 v[84:85], v[84:85], v[100:101]
	v_pk_add_f32 v[86:87], v[86:87], v[102:103]
	v_pk_mul_f32 v[80:81], v[80:81], s[6:7] op_sel_hi:[1,0]
	v_pk_mul_f32 v[82:83], v[82:83], s[6:7] op_sel_hi:[1,0]
	v_pk_mul_f32 v[84:85], v[84:85], s[6:7] op_sel_hi:[1,0]
	v_pk_mul_f32 v[86:87], v[86:87], s[6:7] op_sel_hi:[1,0]
	v_exp_f32_e32 v80, v80
	v_exp_f32_e32 v81, v81
	v_exp_f32_e32 v82, v82
	v_exp_f32_e32 v83, v83
	v_exp_f32_e32 v84, v84
	v_exp_f32_e32 v85, v85
	v_exp_f32_e32 v86, v86
	v_exp_f32_e32 v87, v87
	v_pk_add_f32 v[88:89], v[88:89], v[208:209]
	v_pk_add_f32 v[90:91], v[90:91], v[210:211]
	v_pk_add_f32 v[92:93], v[92:93], v[212:213]
	v_pk_add_f32 v[94:95], v[94:95], v[214:215]
	v_pk_add_f32 v[80:81], v[80:81], s[100:101] op_sel_hi:[1,0]
	v_pk_add_f32 v[82:83], v[82:83], s[100:101] op_sel_hi:[1,0]
	v_pk_add_f32 v[84:85], v[84:85], s[100:101] op_sel_hi:[1,0]
	v_pk_add_f32 v[86:87], v[86:87], s[100:101] op_sel_hi:[1,0]
	v_rcp_f32_e32 v80, v80
	v_rcp_f32_e32 v81, v81
	v_rcp_f32_e32 v82, v82
	v_rcp_f32_e32 v83, v83
	v_rcp_f32_e32 v84, v84
	v_rcp_f32_e32 v85, v85
	v_rcp_f32_e32 v86, v86
	v_rcp_f32_e32 v87, v87
	v_pk_mul_f32 v[88:89], v[88:89], s[6:7] op_sel_hi:[1,0]
	v_pk_mul_f32 v[90:91], v[90:91], s[6:7] op_sel_hi:[1,0]
	v_pk_mul_f32 v[92:93], v[92:93], s[6:7] op_sel_hi:[1,0]
	v_pk_mul_f32 v[94:95], v[94:95], s[6:7] op_sel_hi:[1,0]
	v_pk_mul_f32 v[80:81], v[80:81], s[98:99] op_sel_hi:[1,0]
	v_pk_mul_f32 v[82:83], v[82:83], s[98:99] op_sel_hi:[1,0]
	v_pk_mul_f32 v[84:85], v[84:85], s[98:99] op_sel_hi:[1,0]
	v_pk_mul_f32 v[86:87], v[86:87], s[98:99] op_sel_hi:[1,0]
	v_pk_mul_f32 v[80:81], v[216:217], v[80:81]
	v_pk_mul_f32 v[82:83], v[218:219], v[82:83]
	v_pk_mul_f32 v[84:85], v[220:221], v[84:85]
	v_pk_mul_f32 v[86:87], v[222:223], v[86:87]
	v_pk_mul_f32 v[80:81], v[80:81], s[10:11] op_sel_hi:[1,0]
	v_pk_mul_f32 v[82:83], v[82:83], s[10:11] op_sel_hi:[1,0]
	v_pk_mul_f32 v[84:85], v[84:85], s[10:11] op_sel_hi:[1,0]
	v_pk_mul_f32 v[86:87], v[86:87], s[10:11] op_sel_hi:[1,0]
	v_exp_f32_e32 v80, v80
	v_exp_f32_e32 v81, v81
	v_exp_f32_e32 v82, v82
	v_exp_f32_e32 v83, v83
	v_exp_f32_e32 v84, v84
	v_exp_f32_e32 v85, v85
	v_exp_f32_e32 v86, v86
	v_exp_f32_e32 v87, v87
	v_exp_f32_e32 v88, v88
	v_exp_f32_e32 v89, v89
	v_exp_f32_e32 v90, v90
	v_exp_f32_e32 v91, v91
	v_exp_f32_e32 v92, v92
	v_exp_f32_e32 v93, v93
	v_exp_f32_e32 v94, v94
	v_exp_f32_e32 v95, v95
	v_pk_fma_f32 v[96:97], v[80:81], v[80:81], s[100:101] op_sel_hi:[1,1,0] neg_lo:[1,0,0] neg_hi:[1,0,0]
	v_pk_fma_f32 v[98:99], v[82:83], v[82:83], s[100:101] op_sel_hi:[1,1,0] neg_lo:[1,0,0] neg_hi:[1,0,0]
	v_pk_fma_f32 v[100:101], v[84:85], v[84:85], s[100:101] op_sel_hi:[1,1,0] neg_lo:[1,0,0] neg_hi:[1,0,0]
	v_pk_fma_f32 v[102:103], v[86:87], v[86:87], s[100:101] op_sel_hi:[1,1,0] neg_lo:[1,0,0] neg_hi:[1,0,0]
	v_max_f32_e32 v96, 0, v96
	v_max_f32_e32 v97, 0, v97
	v_max_f32_e32 v98, 0, v98
	v_max_f32_e32 v99, 0, v99
	v_max_f32_e32 v100, 0, v100
	v_max_f32_e32 v101, 0, v101
	v_max_f32_e32 v102, 0, v102
	v_max_f32_e32 v103, 0, v103
	v_pk_add_f32 v[88:89], v[88:89], s[100:101] op_sel_hi:[1,0]
	v_pk_add_f32 v[90:91], v[90:91], s[100:101] op_sel_hi:[1,0]
	v_pk_add_f32 v[92:93], v[92:93], s[100:101] op_sel_hi:[1,0]
	v_pk_add_f32 v[94:95], v[94:95], s[100:101] op_sel_hi:[1,0]
	v_cmp_gt_f32_e64 s[16:17], s89, v96
	v_cmp_gt_f32_e64 s[18:19], s89, v97
	v_cmp_gt_f32_e64 s[20:21], s89, v98
	v_cmp_gt_f32_e64 s[22:23], s89, v99
	v_cndmask_b32_e64 v216, 1.0, v2, s[16:17]
	v_cndmask_b32_e64 v208, 1.0, v3, s[16:17]
	v_cndmask_b32_e64 v217, 1.0, v2, s[18:19]
	v_cndmask_b32_e64 v209, 1.0, v3, s[18:19]
	v_cndmask_b32_e64 v218, 1.0, v2, s[20:21]
	v_cndmask_b32_e64 v210, 1.0, v3, s[20:21]
	v_cndmask_b32_e64 v219, 1.0, v2, s[22:23]
	v_cndmask_b32_e64 v211, 1.0, v3, s[22:23]
	v_cmp_gt_f32_e64 s[16:17], s89, v100
	v_cmp_gt_f32_e64 s[18:19], s89, v101
	v_cmp_gt_f32_e64 s[20:21], s89, v102
; #define LAS __attribute__((address_space(3)))
; __device__ __forceinline__ float sigmoidf_(float x) { return __builtin_amdgcn_rcpf(1.f + __expf(-x)); }
; __device__ __forceinline__ void lru_chain(unsigned char* ws_, const float* const* in_, int l_, LAS unsigned char* lds, int tid, int bid, int G) {
;     ...
;                       da = __builtin_amdgcn_mfma_f32_16x16x32_bf16(fa, bfr[c], da, 0, 0, 0); dx = __builtin_amdgcn_mfma_f32_16x16x32_bf16(fx, bfr[c], dx, 0, 0, 0); }
;                   const int ch = 16 * ot + 4 * kq;
;                   const f32x4 ba4 = *(const LAS f32x4*)(PRM + ch), bx4 = *(const LAS f32x4*)(PRM + 64 + ch), sp4 = *(const LAS f32x4*)(PRM + 128 + ch);
;                   const f32x4 u4 = *(const LAS f32x4*)(B_ + tok * 68 + ch); f32x4 a4, b4;
; #pragma unroll
;                   for (int e = 0; e < 4; ++e) { const float rg = sigmoidf_(da[e] + ba4[e]), ig = sigmoidf_(dx[e] + bx4[e]); const float la = -8.0f * rg * sp4[e];
;                       const float av_ = __expf(la); a4[e] = av_; b4[e] = sqrtf(fmaxf(1.0f - av_ * av_, 0.f)) * ig * u4[e]; }
;                   *(LAS f32x4*)(A_ + tok * 68 + ch) = a4; *(LAS f32x4*)(B_ + tok * 68 + ch) = b4; } }
	v_cmp_gt_f32_e64 s[22:23], s89, v103
	v_cndmask_b32_e64 v220, 1.0, v2, s[16:17]
	v_cndmask_b32_e64 v212, 1.0, v3, s[16:17]
	v_cndmask_b32_e64 v221, 1.0, v2, s[18:19]
	v_cndmask_b32_e64 v213, 1.0, v3, s[18:19]
	v_cndmask_b32_e64 v222, 1.0, v2, s[20:21]
	v_cndmask_b32_e64 v214, 1.0, v3, s[20:21]
	v_cndmask_b32_e64 v223, 1.0, v2, s[22:23]
	v_cndmask_b32_e64 v215, 1.0, v3, s[22:23]
	v_pk_mul_f32 v[96:97], v[96:97], v[216:217]
	v_pk_mul_f32 v[98:99], v[98:99], v[218:219]
	v_pk_mul_f32 v[100:101], v[100:101], v[220:221]
	v_pk_mul_f32 v[102:103], v[102:103], v[222:223]
	v_sqrt_f32_e32 v216, v96
	v_sqrt_f32_e32 v217, v97
	v_sqrt_f32_e32 v218, v98
	v_sqrt_f32_e32 v219, v99
	v_sqrt_f32_e32 v220, v100
	v_sqrt_f32_e32 v221, v101
	v_sqrt_f32_e32 v222, v102
	v_sqrt_f32_e32 v223, v103
	v_rcp_f32_e32 v88, v88
	v_rcp_f32_e32 v89, v89
	v_rcp_f32_e32 v90, v90
	v_rcp_f32_e32 v91, v91
	v_rcp_f32_e32 v92, v92
	v_rcp_f32_e32 v93, v93
	v_rcp_f32_e32 v94, v94
	v_rcp_f32_e32 v95, v95
	v_add_u32_e32 v236, -1, v216
	v_add_u32_e32 v237, -1, v217
	v_add_u32_e32 v238, -1, v218
	v_add_u32_e32 v239, -1, v219
	v_add_u32_e32 v240, -1, v220
	v_add_u32_e32 v241, -1, v221
	v_add_u32_e32 v242, -1, v222
	v_add_u32_e32 v243, -1, v223
	v_pk_fma_f32 v[244:245], v[236:237], v[216:217], v[96:97] neg_lo:[1,0,0] neg_hi:[1,0,0]
	v_pk_fma_f32 v[246:247], v[238:239], v[218:219], v[98:99] neg_lo:[1,0,0] neg_hi:[1,0,0]
	v_pk_fma_f32 v[248:249], v[240:241], v[220:221], v[100:101] neg_lo:[1,0,0] neg_hi:[1,0,0]
	v_pk_fma_f32 v[250:251], v[242:243], v[222:223], v[102:103] neg_lo:[1,0,0] neg_hi:[1,0,0]
	v_add_u32_e32 v180, 1, v216
	v_add_u32_e32 v181, 1, v217
	v_add_u32_e32 v182, 1, v218
	v_add_u32_e32 v183, 1, v219
	v_add_u32_e32 v232, 1, v220
	v_add_u32_e32 v233, 1, v221
	v_add_u32_e32 v234, 1, v222
	v_add_u32_e32 v235, 1, v223
	v_cmp_ge_f32_e64 s[16:17], 0, v244
	v_cmp_ge_f32_e64 s[18:19], 0, v245
	v_cmp_ge_f32_e64 s[20:21], 0, v246
	v_cmp_ge_f32_e64 s[22:23], 0, v247
	v_cndmask_b32_e64 v236, v216, v236, s[16:17]
	v_cndmask_b32_e64 v237, v217, v237, s[18:19]
	v_cndmask_b32_e64 v238, v218, v238, s[20:21]
	v_cndmask_b32_e64 v239, v219, v239, s[22:23]
	v_cmp_ge_f32_e64 s[16:17], 0, v248
	v_cmp_ge_f32_e64 s[18:19], 0, v249
	v_cmp_ge_f32_e64 s[20:21], 0, v250
	v_cmp_ge_f32_e64 s[22:23], 0, v251
	v_cndmask_b32_e64 v240, v220, v240, s[16:17]
	v_cndmask_b32_e64 v241, v221, v241, s[18:19]
	v_cndmask_b32_e64 v242, v222, v242, s[20:21]
	v_cndmask_b32_e64 v243, v223, v243, s[22:23]
	v_pk_fma_f32 v[244:245], v[180:181], v[216:217], v[96:97] neg_lo:[1,0,0] neg_hi:[1,0,0]
	v_pk_fma_f32 v[246:247], v[182:183], v[218:219], v[98:99] neg_lo:[1,0,0] neg_hi:[1,0,0]
	v_pk_fma_f32 v[248:249], v[232:233], v[220:221], v[100:101] neg_lo:[1,0,0] neg_hi:[1,0,0]
	v_pk_fma_f32 v[250:251], v[234:235], v[222:223], v[102:103] neg_lo:[1,0,0] neg_hi:[1,0,0]
	v_cmp_lt_f32_e64 s[16:17], 0, v244
	v_cmp_lt_f32_e64 s[18:19], 0, v245
	v_cmp_lt_f32_e64 s[20:21], 0, v246
	v_cmp_lt_f32_e64 s[22:23], 0, v247
	v_cndmask_b32_e64 v236, v236, v180, s[16:17]
	v_cndmask_b32_e64 v237, v237, v181, s[18:19]
	v_cndmask_b32_e64 v238, v238, v182, s[20:21]
	v_cndmask_b32_e64 v239, v239, v183, s[22:23]
	v_cmp_lt_f32_e64 s[16:17], 0, v248
	v_cmp_lt_f32_e64 s[18:19], 0, v249
	v_cmp_lt_f32_e64 s[20:21], 0, v250
	v_cmp_lt_f32_e64 s[22:23], 0, v251
	v_cndmask_b32_e64 v240, v240, v232, s[16:17]
	v_cndmask_b32_e64 v241, v241, v233, s[18:19]
	v_cndmask_b32_e64 v242, v242, v234, s[20:21]
	v_cndmask_b32_e64 v243, v243, v235, s[22:23]
	v_pk_mul_f32 v[236:237], v[236:237], v[208:209]
	v_pk_mul_f32 v[238:239], v[238:239], v[210:211]
	v_pk_mul_f32 v[240:241], v[240:241], v[212:213]
	v_pk_mul_f32 v[242:243], v[242:243], v[214:215]
	v_cmp_class_f32_e64 s[16:17], v96, v175
	v_cmp_class_f32_e64 s[18:19], v97, v175
	v_cmp_class_f32_e64 s[20:21], v98, v175
	v_cmp_class_f32_e64 s[22:23], v99, v175
	v_cndmask_b32_e64 v236, v236, v96, s[16:17]
	v_cndmask_b32_e64 v237, v237, v97, s[18:19]
	v_cndmask_b32_e64 v238, v238, v98, s[20:21]
	v_cndmask_b32_e64 v239, v239, v99, s[22:23]
	v_cmp_class_f32_e64 s[16:17], v100, v175
	v_cmp_class_f32_e64 s[18:19], v101, v175
	v_cmp_class_f32_e64 s[20:21], v102, v175
	v_cmp_class_f32_e64 s[22:23], v103, v175
	v_cndmask_b32_e64 v240, v240, v100, s[16:17]
	v_cndmask_b32_e64 v241, v241, v101, s[18:19]
	v_cndmask_b32_e64 v242, v242, v102, s[20:21]
	v_cndmask_b32_e64 v243, v243, v103, s[22:23]
	v_pk_mul_f32 v[88:89], v[88:89], v[236:237]
	v_pk_mul_f32 v[90:91], v[90:91], v[238:239]
	v_pk_mul_f32 v[92:93], v[92:93], v[240:241]
	v_pk_mul_f32 v[94:95], v[94:95], v[242:243]
	v_pk_mul_f32 v[88:89], v[224:225], v[88:89]
	v_pk_mul_f32 v[90:91], v[226:227], v[90:91]
	v_pk_mul_f32 v[92:93], v[228:229], v[92:93]
	v_pk_mul_f32 v[94:95], v[230:231], v[94:95]
	ds_write_b128 v169, v[80:83] offset:18432
	ds_write_b128 v169, v[88:91] offset:53248
	ds_write_b128 v169, v[84:87] offset:18496
	ds_write_b128 v169, v[92:95] offset:53312
	ds_read_b128 v[236:239], v203 offset:4608
	ds_read_b128 v[244:247], v203 offset:13824
	ds_read_b128 v[180:183], v203 offset:4672
	ds_read_b128 v[240:243], v203 offset:13888
	ds_read_b128 v[96:99], v173
	ds_read_b128 v[208:211], v192
	ds_read_b128 v[216:219], v193
	ds_read_b128 v[224:227], v169 offset:53376
	ds_read_b128 v[100:103], v194
	ds_read_b128 v[212:215], v195
	ds_read_b128 v[220:223], v196
	ds_read_b128 v[228:231], v169 offset:53440
	s_waitcnt lgkmcnt(11)
	v_mfma_f32_16x16x32_bf16 v[80:83], v[236:239], v[76:79], 0
	s_waitcnt lgkmcnt(10)
	v_mfma_f32_16x16x32_bf16 v[88:91], v[244:247], v[76:79], 0
	s_waitcnt lgkmcnt(9)
	v_mfma_f32_16x16x32_bf16 v[80:83], v[180:183], v[72:75], v[80:83]
	s_waitcnt lgkmcnt(8)
; #define LAS __attribute__((address_space(3)))
; __device__ __forceinline__ float sigmoidf_(float x) { return __builtin_amdgcn_rcpf(1.f + __expf(-x)); }
; __device__ __forceinline__ void lru_chain(unsigned char* ws_, const float* const* in_, int l_, LAS unsigned char* lds, int tid, int bid, int G) {
;     ...
;                       da = __builtin_amdgcn_mfma_f32_16x16x32_bf16(fa, bfr[c], da, 0, 0, 0); dx = __builtin_amdgcn_mfma_f32_16x16x32_bf16(fx, bfr[c], dx, 0, 0, 0); }
;                   const int ch = 16 * ot + 4 * kq;
;                   const f32x4 ba4 = *(const LAS f32x4*)(PRM + ch), bx4 = *(const LAS f32x4*)(PRM + 64 + ch), sp4 = *(const LAS f32x4*)(PRM + 128 + ch);
;                   const f32x4 u4 = *(const LAS f32x4*)(B_ + tok * 68 + ch); f32x4 a4, b4;
; #pragma unroll
;                   for (int e = 0; e < 4; ++e) { const float rg = sigmoidf_(da[e] + ba4[e]), ig = sigmoidf_(dx[e] + bx4[e]); const float la = -8.0f * rg * sp4[e];
;                       const float av_ = __expf(la); a4[e] = av_; b4[e] = sqrtf(fmaxf(1.0f - av_ * av_, 0.f)) * ig * u4[e]; }
;                   *(LAS f32x4*)(A_ + tok * 68 + ch) = a4; *(LAS f32x4*)(B_ + tok * 68 + ch) = b4; } }
	v_mfma_f32_16x16x32_bf16 v[88:91], v[240:243], v[72:75], v[88:91]
	ds_read_b128 v[236:239], v203 offset:6912
	ds_read_b128 v[244:247], v203 offset:16128
	ds_read_b128 v[180:183], v203 offset:6976
	ds_read_b128 v[240:243], v203 offset:16192
	s_waitcnt lgkmcnt(3)
	v_mfma_f32_16x16x32_bf16 v[84:87], v[236:239], v[76:79], 0
	s_waitcnt lgkmcnt(2)
	v_mfma_f32_16x16x32_bf16 v[92:95], v[244:247], v[76:79], 0
	s_waitcnt lgkmcnt(1)
	v_mfma_f32_16x16x32_bf16 v[84:87], v[180:183], v[72:75], v[84:87]
	s_waitcnt lgkmcnt(0)
	v_mfma_f32_16x16x32_bf16 v[92:95], v[240:243], v[72:75], v[92:95]
	s_waitcnt lgkmcnt(0)
	s_nop 7
	v_pk_add_f32 v[80:81], v[80:81], v[96:97]
	v_pk_add_f32 v[82:83], v[82:83], v[98:99]
	v_pk_add_f32 v[84:85], v[84:85], v[100:101]
	v_pk_add_f32 v[86:87], v[86:87], v[102:103]
	v_pk_mul_f32 v[80:81], v[80:81], s[6:7] op_sel_hi:[1,0]
	v_pk_mul_f32 v[82:83], v[82:83], s[6:7] op_sel_hi:[1,0]
	v_pk_mul_f32 v[84:85], v[84:85], s[6:7] op_sel_hi:[1,0]
	v_pk_mul_f32 v[86:87], v[86:87], s[6:7] op_sel_hi:[1,0]
	v_exp_f32_e32 v80, v80
	v_exp_f32_e32 v81, v81
	v_exp_f32_e32 v82, v82
	v_exp_f32_e32 v83, v83
	v_exp_f32_e32 v84, v84
	v_exp_f32_e32 v85, v85
	v_exp_f32_e32 v86, v86
	v_exp_f32_e32 v87, v87
	v_pk_add_f32 v[88:89], v[88:89], v[208:209]
	v_pk_add_f32 v[90:91], v[90:91], v[210:211]
	v_pk_add_f32 v[92:93], v[92:93], v[212:213]
	v_pk_add_f32 v[94:95], v[94:95], v[214:215]
	v_pk_add_f32 v[80:81], v[80:81], s[100:101] op_sel_hi:[1,0]
	v_pk_add_f32 v[82:83], v[82:83], s[100:101] op_sel_hi:[1,0]
	v_pk_add_f32 v[84:85], v[84:85], s[100:101] op_sel_hi:[1,0]
	v_pk_add_f32 v[86:87], v[86:87], s[100:101] op_sel_hi:[1,0]
	v_rcp_f32_e32 v80, v80
	v_rcp_f32_e32 v81, v81
	v_rcp_f32_e32 v82, v82
	v_rcp_f32_e32 v83, v83
	v_rcp_f32_e32 v84, v84
	v_rcp_f32_e32 v85, v85
	v_rcp_f32_e32 v86, v86
	v_rcp_f32_e32 v87, v87
	v_pk_mul_f32 v[88:89], v[88:89], s[6:7] op_sel_hi:[1,0]
	v_pk_mul_f32 v[90:91], v[90:91], s[6:7] op_sel_hi:[1,0]
	v_pk_mul_f32 v[92:93], v[92:93], s[6:7] op_sel_hi:[1,0]
	v_pk_mul_f32 v[94:95], v[94:95], s[6:7] op_sel_hi:[1,0]
	v_pk_mul_f32 v[80:81], v[80:81], s[98:99] op_sel_hi:[1,0]
	v_pk_mul_f32 v[82:83], v[82:83], s[98:99] op_sel_hi:[1,0]
	v_pk_mul_f32 v[84:85], v[84:85], s[98:99] op_sel_hi:[1,0]
	v_pk_mul_f32 v[86:87], v[86:87], s[98:99] op_sel_hi:[1,0]
	v_pk_mul_f32 v[80:81], v[216:217], v[80:81]
	v_pk_mul_f32 v[82:83], v[218:219], v[82:83]
	v_pk_mul_f32 v[84:85], v[220:221], v[84:85]
	v_pk_mul_f32 v[86:87], v[222:223], v[86:87]
	v_pk_mul_f32 v[80:81], v[80:81], s[10:11] op_sel_hi:[1,0]
	v_pk_mul_f32 v[82:83], v[82:83], s[10:11] op_sel_hi:[1,0]
	v_pk_mul_f32 v[84:85], v[84:85], s[10:11] op_sel_hi:[1,0]
	v_pk_mul_f32 v[86:87], v[86:87], s[10:11] op_sel_hi:[1,0]
	v_exp_f32_e32 v80, v80
	v_exp_f32_e32 v81, v81
	v_exp_f32_e32 v82, v82
	v_exp_f32_e32 v83, v83
	v_exp_f32_e32 v84, v84
	v_exp_f32_e32 v85, v85
	v_exp_f32_e32 v86, v86
	v_exp_f32_e32 v87, v87
	v_exp_f32_e32 v88, v88
	v_exp_f32_e32 v89, v89
	v_exp_f32_e32 v90, v90
	v_exp_f32_e32 v91, v91
	v_exp_f32_e32 v92, v92
	v_exp_f32_e32 v93, v93
	v_exp_f32_e32 v94, v94
	v_exp_f32_e32 v95, v95
	v_pk_fma_f32 v[96:97], v[80:81], v[80:81], s[100:101] op_sel_hi:[1,1,0] neg_lo:[1,0,0] neg_hi:[1,0,0]
	v_pk_fma_f32 v[98:99], v[82:83], v[82:83], s[100:101] op_sel_hi:[1,1,0] neg_lo:[1,0,0] neg_hi:[1,0,0]
	v_pk_fma_f32 v[100:101], v[84:85], v[84:85], s[100:101] op_sel_hi:[1,1,0] neg_lo:[1,0,0] neg_hi:[1,0,0]
	v_pk_fma_f32 v[102:103], v[86:87], v[86:87], s[100:101] op_sel_hi:[1,1,0] neg_lo:[1,0,0] neg_hi:[1,0,0]
	v_max_f32_e32 v96, 0, v96
	v_max_f32_e32 v97, 0, v97
	v_max_f32_e32 v98, 0, v98
	v_max_f32_e32 v99, 0, v99
	v_max_f32_e32 v100, 0, v100
	v_max_f32_e32 v101, 0, v101
	v_max_f32_e32 v102, 0, v102
	v_max_f32_e32 v103, 0, v103
	v_pk_add_f32 v[88:89], v[88:89], s[100:101] op_sel_hi:[1,0]
	v_pk_add_f32 v[90:91], v[90:91], s[100:101] op_sel_hi:[1,0]
	v_pk_add_f32 v[92:93], v[92:93], s[100:101] op_sel_hi:[1,0]
	v_pk_add_f32 v[94:95], v[94:95], s[100:101] op_sel_hi:[1,0]
	v_cmp_gt_f32_e64 s[16:17], s89, v96
	v_cmp_gt_f32_e64 s[18:19], s89, v97
	v_cmp_gt_f32_e64 s[20:21], s89, v98
	v_cmp_gt_f32_e64 s[22:23], s89, v99
	v_cndmask_b32_e64 v216, 1.0, v2, s[16:17]
	v_cndmask_b32_e64 v208, 1.0, v3, s[16:17]
	v_cndmask_b32_e64 v217, 1.0, v2, s[18:19]
	v_cndmask_b32_e64 v209, 1.0, v3, s[18:19]
	v_cndmask_b32_e64 v218, 1.0, v2, s[20:21]
	v_cndmask_b32_e64 v210, 1.0, v3, s[20:21]
	v_cndmask_b32_e64 v219, 1.0, v2, s[22:23]
	v_cndmask_b32_e64 v211, 1.0, v3, s[22:23]
	v_cmp_gt_f32_e64 s[16:17], s89, v100
	v_cmp_gt_f32_e64 s[18:19], s89, v101
	v_cmp_gt_f32_e64 s[20:21], s89, v102
	v_cmp_gt_f32_e64 s[22:23], s89, v103
	v_cndmask_b32_e64 v220, 1.0, v2, s[16:17]
	v_cndmask_b32_e64 v212, 1.0, v3, s[16:17]
	v_cndmask_b32_e64 v221, 1.0, v2, s[18:19]
	v_cndmask_b32_e64 v213, 1.0, v3, s[18:19]
	v_cndmask_b32_e64 v222, 1.0, v2, s[20:21]
	v_cndmask_b32_e64 v214, 1.0, v3, s[20:21]
	v_cndmask_b32_e64 v223, 1.0, v2, s[22:23]
	v_cndmask_b32_e64 v215, 1.0, v3, s[22:23]
	v_pk_mul_f32 v[96:97], v[96:97], v[216:217]
	v_pk_mul_f32 v[98:99], v[98:99], v[218:219]
	v_pk_mul_f32 v[100:101], v[100:101], v[220:221]
	v_pk_mul_f32 v[102:103], v[102:103], v[222:223]
	v_sqrt_f32_e32 v216, v96
	v_sqrt_f32_e32 v217, v97
	v_sqrt_f32_e32 v218, v98
	v_sqrt_f32_e32 v219, v99
	v_sqrt_f32_e32 v220, v100
	v_sqrt_f32_e32 v221, v101
	v_sqrt_f32_e32 v222, v102
	v_sqrt_f32_e32 v223, v103
	v_rcp_f32_e32 v88, v88
	v_rcp_f32_e32 v89, v89
	v_rcp_f32_e32 v90, v90
	v_rcp_f32_e32 v91, v91
	v_rcp_f32_e32 v92, v92
	v_rcp_f32_e32 v93, v93
	v_rcp_f32_e32 v94, v94
	v_rcp_f32_e32 v95, v95
	v_add_u32_e32 v236, -1, v216
	v_add_u32_e32 v237, -1, v217
	v_add_u32_e32 v238, -1, v218
; #define LAS __attribute__((address_space(3)))
; __device__ __forceinline__ float sigmoidf_(float x) { return __builtin_amdgcn_rcpf(1.f + __expf(-x)); }
; __device__ __forceinline__ void lru_chain(unsigned char* ws_, const float* const* in_, int l_, LAS unsigned char* lds, int tid, int bid, int G) {
;     ...
;                   const int ch = 16 * ot + 4 * kq;
;                   const f32x4 ba4 = *(const LAS f32x4*)(PRM + ch), bx4 = *(const LAS f32x4*)(PRM + 64 + ch), sp4 = *(const LAS f32x4*)(PRM + 128 + ch);
;                   const f32x4 u4 = *(const LAS f32x4*)(B_ + tok * 68 + ch); f32x4 a4, b4;
; #pragma unroll
;                   for (int e = 0; e < 4; ++e) { const float rg = sigmoidf_(da[e] + ba4[e]), ig = sigmoidf_(dx[e] + bx4[e]); const float la = -8.0f * rg * sp4[e];
;                       const float av_ = __expf(la); a4[e] = av_; b4[e] = sqrtf(fmaxf(1.0f - av_ * av_, 0.f)) * ig * u4[e]; }
;                   *(LAS f32x4*)(A_ + tok * 68 + ch) = a4; *(LAS f32x4*)(B_ + tok * 68 + ch) = b4; } }
;             __syncthreads();
;             float av[16], bv[16]; float hh = 0.f, aa = 1.f;
; #pragma unroll
;             for (int i = 0; i < 16; ++i) { av[i] = A_[(16 * w + i) * 68 + lane]; bv[i] = B_[(16 * w + i) * 68 + lane]; hh = av[i] * hh + bv[i]; aa *= av[i]; }
;             SA[w * 64 + lane] = aa; SB[w * 64 + lane] = hh;
;             __syncthreads();
;             float hin = CAR[(chunk & 1) * 64 + lane];
;             for (int sgi = 0; sgi < w; ++sgi) hin = SA[sgi * 64 + lane] * hin + SB[sgi * 64 + lane];
	v_add_u32_e32 v239, -1, v219
	v_add_u32_e32 v240, -1, v220
	v_add_u32_e32 v241, -1, v221
	v_add_u32_e32 v242, -1, v222
	v_add_u32_e32 v243, -1, v223
	v_pk_fma_f32 v[244:245], v[236:237], v[216:217], v[96:97] neg_lo:[1,0,0] neg_hi:[1,0,0]
	v_pk_fma_f32 v[246:247], v[238:239], v[218:219], v[98:99] neg_lo:[1,0,0] neg_hi:[1,0,0]
	v_pk_fma_f32 v[248:249], v[240:241], v[220:221], v[100:101] neg_lo:[1,0,0] neg_hi:[1,0,0]
	v_pk_fma_f32 v[250:251], v[242:243], v[222:223], v[102:103] neg_lo:[1,0,0] neg_hi:[1,0,0]
	v_add_u32_e32 v180, 1, v216
	v_add_u32_e32 v181, 1, v217
	v_add_u32_e32 v182, 1, v218
	v_add_u32_e32 v183, 1, v219
	v_add_u32_e32 v232, 1, v220
	v_add_u32_e32 v233, 1, v221
	v_add_u32_e32 v234, 1, v222
	v_add_u32_e32 v235, 1, v223
	v_cmp_ge_f32_e64 s[16:17], 0, v244
	v_cmp_ge_f32_e64 s[18:19], 0, v245
	v_cmp_ge_f32_e64 s[20:21], 0, v246
	v_cmp_ge_f32_e64 s[22:23], 0, v247
	v_cndmask_b32_e64 v236, v216, v236, s[16:17]
	v_cndmask_b32_e64 v237, v217, v237, s[18:19]
	v_cndmask_b32_e64 v238, v218, v238, s[20:21]
	v_cndmask_b32_e64 v239, v219, v239, s[22:23]
	v_cmp_ge_f32_e64 s[16:17], 0, v248
	v_cmp_ge_f32_e64 s[18:19], 0, v249
	v_cmp_ge_f32_e64 s[20:21], 0, v250
	v_cmp_ge_f32_e64 s[22:23], 0, v251
	v_cndmask_b32_e64 v240, v220, v240, s[16:17]
	v_cndmask_b32_e64 v241, v221, v241, s[18:19]
	v_cndmask_b32_e64 v242, v222, v242, s[20:21]
	v_cndmask_b32_e64 v243, v223, v243, s[22:23]
	v_pk_fma_f32 v[244:245], v[180:181], v[216:217], v[96:97] neg_lo:[1,0,0] neg_hi:[1,0,0]
	v_pk_fma_f32 v[246:247], v[182:183], v[218:219], v[98:99] neg_lo:[1,0,0] neg_hi:[1,0,0]
	v_pk_fma_f32 v[248:249], v[232:233], v[220:221], v[100:101] neg_lo:[1,0,0] neg_hi:[1,0,0]
	v_pk_fma_f32 v[250:251], v[234:235], v[222:223], v[102:103] neg_lo:[1,0,0] neg_hi:[1,0,0]
	v_cmp_lt_f32_e64 s[16:17], 0, v244
	v_cmp_lt_f32_e64 s[18:19], 0, v245
	v_cmp_lt_f32_e64 s[20:21], 0, v246
	v_cmp_lt_f32_e64 s[22:23], 0, v247
	v_cndmask_b32_e64 v236, v236, v180, s[16:17]
	v_cndmask_b32_e64 v237, v237, v181, s[18:19]
	v_cndmask_b32_e64 v238, v238, v182, s[20:21]
	v_cndmask_b32_e64 v239, v239, v183, s[22:23]
	v_cmp_lt_f32_e64 s[16:17], 0, v248
	v_cmp_lt_f32_e64 s[18:19], 0, v249
	v_cmp_lt_f32_e64 s[20:21], 0, v250
	v_cmp_lt_f32_e64 s[22:23], 0, v251
	v_cndmask_b32_e64 v240, v240, v232, s[16:17]
	v_cndmask_b32_e64 v241, v241, v233, s[18:19]
	v_cndmask_b32_e64 v242, v242, v234, s[20:21]
	v_cndmask_b32_e64 v243, v243, v235, s[22:23]
	v_pk_mul_f32 v[236:237], v[236:237], v[208:209]
	v_pk_mul_f32 v[238:239], v[238:239], v[210:211]
	v_pk_mul_f32 v[240:241], v[240:241], v[212:213]
	v_pk_mul_f32 v[242:243], v[242:243], v[214:215]
	v_cmp_class_f32_e64 s[16:17], v96, v175
	v_cmp_class_f32_e64 s[18:19], v97, v175
	v_cmp_class_f32_e64 s[20:21], v98, v175
	v_cmp_class_f32_e64 s[22:23], v99, v175
	v_cndmask_b32_e64 v236, v236, v96, s[16:17]
	v_cndmask_b32_e64 v237, v237, v97, s[18:19]
	v_cndmask_b32_e64 v238, v238, v98, s[20:21]
	v_cndmask_b32_e64 v239, v239, v99, s[22:23]
	v_cmp_class_f32_e64 s[16:17], v100, v175
	v_cmp_class_f32_e64 s[18:19], v101, v175
	v_cmp_class_f32_e64 s[20:21], v102, v175
	v_cmp_class_f32_e64 s[22:23], v103, v175
	v_cndmask_b32_e64 v240, v240, v100, s[16:17]
	v_cndmask_b32_e64 v241, v241, v101, s[18:19]
	v_cndmask_b32_e64 v242, v242, v102, s[20:21]
	v_cndmask_b32_e64 v243, v243, v103, s[22:23]
	v_pk_mul_f32 v[88:89], v[88:89], v[236:237]
	v_pk_mul_f32 v[90:91], v[90:91], v[238:239]
	v_pk_mul_f32 v[92:93], v[92:93], v[240:241]
	v_pk_mul_f32 v[94:95], v[94:95], v[242:243]
	v_pk_mul_f32 v[88:89], v[224:225], v[88:89]
	v_pk_mul_f32 v[90:91], v[226:227], v[90:91]
	v_pk_mul_f32 v[92:93], v[228:229], v[92:93]
	v_pk_mul_f32 v[94:95], v[230:231], v[94:95]
	ds_write_b128 v169, v[80:83] offset:18560
	ds_write_b128 v169, v[88:91] offset:53376
	ds_write_b128 v169, v[84:87] offset:18624
	ds_write_b128 v169, v[92:95] offset:53440
	v_add_u32_e32 v1, 0x4800, v197
	v_add_u32_e32 v2, 0xd000, v197
	v_add_u32_e32 v102, 0xdc00, v197
	s_waitcnt lgkmcnt(0)
	ds_read2_b32 v[100:101], v1 offset1:68
	ds_read2_b32 v[96:97], v2 offset1:68
	ds_read2_b32 v[98:99], v1 offset0:136 offset1:204
	ds_read2_b32 v[92:93], v2 offset0:136 offset1:204
	s_andn2_b64 vcc, exec, s[48:49]
	s_waitcnt lgkmcnt(3)
	v_mul_f32_e32 v72, v100, v101
	s_waitcnt lgkmcnt(2)
	v_fma_f32 v3, 0, v100, v96
	v_fma_f32 v3, v3, v101, v97
	s_waitcnt lgkmcnt(0)
	v_fma_f32 v1, v3, v98, v92
	v_add_u32_e32 v3, 0x4c00, v197
	ds_read2_b32 v[94:95], v3 offset0:16 offset1:84
	v_mul_f32_e32 v2, v72, v98
	v_add_u32_e32 v72, 0xd400, v197
	ds_read2_b32 v[88:89], v72 offset0:16 offset1:84
	ds_read2_b32 v[90:91], v3 offset0:152 offset1:220
	ds_read2_b32 v[84:85], v72 offset0:152 offset1:220
	v_add_u32_e32 v3, 0x5000, v197
	v_mul_f32_e32 v2, v2, v99
	ds_read2_b32 v[86:87], v3 offset0:32 offset1:100
	s_waitcnt lgkmcnt(4)
	v_mul_f32_e32 v2, v2, v94
	v_mul_f32_e32 v2, v2, v95
	v_add_u32_e32 v72, 0xd800, v197
	s_waitcnt lgkmcnt(2)
	v_mul_f32_e32 v2, v2, v90
	ds_read2_b32 v[80:81], v72 offset0:32 offset1:100
	ds_read2_b32 v[82:83], v3 offset0:168 offset1:236
	ds_read2_b32 v[76:77], v72 offset0:168 offset1:236
	v_add_u32_e32 v3, 0x5400, v197
	v_fma_f32 v1, v1, v99, v93
	v_mul_f32_e32 v2, v2, v91
	ds_read2_b32 v[78:79], v3 offset0:48 offset1:116
	v_fma_f32 v1, v1, v94, v88
	s_waitcnt lgkmcnt(4)
	v_mul_f32_e32 v2, v2, v86
	v_fma_f32 v1, v1, v95, v89
	v_mul_f32_e32 v2, v2, v87
	v_fma_f32 v1, v1, v90, v84
	s_waitcnt lgkmcnt(2)
	v_mul_f32_e32 v2, v2, v82
	v_fma_f32 v1, v1, v91, v85
	v_mul_f32_e32 v2, v2, v83
	ds_read2_b32 v[72:73], v102 offset0:48 offset1:116
	v_fma_f32 v1, v1, v86, v80
	s_waitcnt lgkmcnt(1)
	v_mul_f32_e32 v2, v2, v78
	v_fma_f32 v1, v1, v87, v81
	v_mul_f32_e32 v103, v2, v79
	ds_read2_b32 v[74:75], v3 offset0:184 offset1:252
	ds_read2_b32 v[2:3], v102 offset0:184 offset1:252
	v_fma_f32 v1, v1, v82, v76
	v_fma_f32 v1, v1, v83, v77
	s_waitcnt lgkmcnt(2)
	v_fma_f32 v1, v1, v78, v72
	v_fma_f32 v1, v1, v79, v73
	s_waitcnt lgkmcnt(0)
	v_fma_f32 v1, v1, v74, v2
	v_mul_f32_e32 v102, v103, v74
	v_fma_f32 v1, v1, v75, v3
	v_mul_f32_e32 v102, v102, v75
	ds_write_b32 v162, v102
	ds_write_b32 v163, v1
	v_lshl_add_u32 v1, s2, 2, v159
	s_waitcnt lgkmcnt(0)
	s_barrier
	ds_read_b32 v1, v1
	v_mov_b32_e32 v102, v198
	s_cbranch_vccnz .LBB0_203
; __device__ __forceinline__ void lru_chain(unsigned char* ws_, const float* const* in_, int l_, LAS unsigned char* lds, int tid, int bid, int G) {
;     ...
;             float hin = CAR[(chunk & 1) * 64 + lane];
;             for (int sgi = 0; sgi < w; ++sgi) hin = SA[sgi * 64 + lane] * hin + SB[sgi * 64 + lane];
;             hh = hin;
.LBB0_202:
	v_add_u32_e32 v103, 0xfffff800, v102
	ds_read_b32 v206, v103
	ds_read_b32 v207, v102
	ds_read_b32 v208, v103 offset:256
	ds_read_b32 v209, v102 offset:256
	ds_read_b32 v210, v103 offset:512
	ds_read_b32 v211, v102 offset:512
	ds_read_b32 v212, v103 offset:768
	ds_read_b32 v213, v102 offset:768
	ds_read_b32 v214, v103 offset:1024
	ds_read_b32 v215, v102 offset:1024
	ds_read_b32 v216, v103 offset:1280
	ds_read_b32 v217, v102 offset:1280
	ds_read_b32 v218, v103 offset:1536
	ds_read_b32 v219, v102 offset:1536
	s_waitcnt lgkmcnt(12)
	v_fma_f32 v1, v1, v206, v207
	s_cmp_eq_u32 s3, 1
	s_cbranch_scc1 .LBB0_203
	s_waitcnt lgkmcnt(10)
	v_fma_f32 v1, v1, v208, v209
	s_cmp_eq_u32 s3, 2
	s_cbranch_scc1 .LBB0_203
	s_waitcnt lgkmcnt(8)
	v_fma_f32 v1, v1, v210, v211
	s_cmp_eq_u32 s3, 3
	s_cbranch_scc1 .LBB0_203
	s_waitcnt lgkmcnt(6)
	v_fma_f32 v1, v1, v212, v213
	s_cmp_eq_u32 s3, 4
	s_cbranch_scc1 .LBB0_203
	s_waitcnt lgkmcnt(4)
	v_fma_f32 v1, v1, v214, v215
	s_cmp_eq_u32 s3, 5
	s_cbranch_scc1 .LBB0_203
	s_waitcnt lgkmcnt(2)
	v_fma_f32 v1, v1, v216, v217
	s_cmp_eq_u32 s3, 6
	s_cbranch_scc1 .LBB0_203
	s_waitcnt lgkmcnt(0)
	v_fma_f32 v1, v1, v218, v219

; #define LAS __attribute__((address_space(3)))
; __device__ __forceinline__ void attn_compute(const MixCtx& X, int a, LAS unsigned char* lds, int tid, const bf16x8 q0, const bf16x8 q1) {
;     const int lane = tid & 63, w = __builtin_amdgcn_readfirstlane(tid >> 6);
;     const int b = a / 96, rem = a % 96, h = rem >> 4, u16 = rem & 15;
;     const int sh = 2 * (h >> 1), dil = 1 << sh, nbm = (16 >> sh) - 1;
;     const int r = u16 >> (4 - sh), n = u16 & nbm;
;     const float slope = exp2f(-8.0f * (float)(h + 1) / 6.0f);
;     const float c1 = 0.125f * LOG2E, c2 = slope * (float)dil * LOG2E;
;     LAS unsigned char* Kl = lds; LAS unsigned char* Vl = lds + 39168;
;     const int j = lane & 15, kq = lane >> 4;
;     const int qi = 16 * w + j; const int qpos = (n * 128 + qi) * dil + r;
;     float s[9][4]; float mx = -1e30f;
;     const int d0 = j + 128 - 4 * kq;
;     float be[4]; const float bstep = 16.0f * c2;
; #pragma unroll
;     for (int e = 0; e < 4; ++e) be[e] = -c2 * (float)(d0 - e);
;     const int nlive0 = (n == 0) ? (8 - w) : 0;
; #pragma unroll
;     for (int tt = 0; tt < 9; ++tt) {
;         if (tt >= nlive0) {
;             const int kt = w + tt; const LAS unsigned char* p = Kl + (16 * kt + j) * 144 + kq * 16;
;             const bf16x8 k0f = *(const LAS bf16x8*)p, k1f = *(const LAS bf16x8*)(p + 64);
;             f32x4 acc = (f32x4){0.f, 0.f, 0.f, 0.f};
;             acc = __builtin_amdgcn_mfma_f32_16x16x32_bf16(k0f, q0, acc, 0, 0, 0);
;             acc = __builtin_amdgcn_mfma_f32_16x16x32_bf16(k1f, q1, acc, 0, 0, 0);
; #pragma unroll
;             for (int e = 0; e < 4; ++e) {
;                 float v = acc[e] * c1 + (be[e] + bstep * (float)tt);
;                 if (tt == 0) { if (d0 - e > 128) v = -1e30f; }
;                 if (tt == 8) { if (d0 - 128 - e < 0) v = -1e30f; }
;                 s[tt][e] = v; mx = fmaxf(mx, v); }
.LBB0_233:
	v_readfirstlane_b32 s4, v67
	s_ashr_i32 s93, s4, 6
	s_mul_hi_i32 s4, s2, 0x2aaaaaab
	s_lshr_b32 s5, s4, 31
	s_ashr_i32 s4, s4, 4
	s_add_i32 s92, s4, s5
	s_mul_i32 s4, s92, 0xffffffa0
	s_add_i32 s4, s2, s4
	s_ashr_i32 s68, s4, 4
	s_add_i32 s5, s68, 1
	v_cvt_f32_i32_e32 v1, s5
	s_and_b32 s63, s68, -2
	s_lshr_b32 s5, 16, s63
	s_and_b32 s4, s4, 15
	v_mul_f32_e32 v1, 0xc1000000, v1
	v_div_scale_f32 v2, s[6:7], s9, s9, v1
	v_rcp_f32_e32 v3, v2
	s_mov_b32 s6, 0xc2fc0000
	s_add_i32 s5, s5, -1
	s_lshl_b32 s26, 1, s63
	v_fma_f32 v52, -v2, v3, 1.0
	v_fmac_f32_e32 v3, v52, v3
	v_div_scale_f32 v52, vcc, v1, s9, v1
	v_mul_f32_e32 v53, v52, v3
	v_fma_f32 v54, -v2, v53, v52
	v_fmac_f32_e32 v53, v54, v3
	v_fma_f32 v2, -v2, v53, v52
	v_div_fmas_f32 v2, v2, v3, v53
	v_div_fixup_f32 v1, v2, s9, v1
	v_cmp_gt_f32_e32 vcc, s6, v1
	v_mov_b32_e32 v2, 0x42800000
	s_and_b32 s5, s5, s4
	v_cndmask_b32_e32 v2, 0, v2, vcc
	v_add_f32_e32 v1, v1, v2
	v_exp_f32_e32 v1, v1
	v_cvt_f32_u32_e32 v2, s26
	s_and_b64 s[6:7], vcc, exec
	s_cselect_b32 s6, 0xffffffc0, 0
	v_ldexp_f32 v1, v1, s6
	s_lshl_b32 s69, s93, 4
	s_sub_i32 s6, 8, s93
	s_cmp_eq_u32 s5, 0
	v_mul_f32_e32 v1, v1, v2
	s_cselect_b32 s6, s6, 0
	v_mul_f32_e32 v2, 0x3fb8aa3b, v1
	s_cmp_lt_i32 s6, 1
	v_pk_mul_f32 v[56:57], v[2:3], v[62:63] op_sel_hi:[0,1] neg_lo:[1,0] neg_hi:[1,0]
	v_pk_mul_f32 v[52:53], v[2:3], v[64:65] op_sel_hi:[0,1] neg_lo:[1,0] neg_hi:[1,0]
	v_mul_f32_e32 v58, 0x41800000, v2
	v_mov_b32_e32 v2, 0xf149f2ca
	s_cselect_b64 s[54:55], -1, 0
	s_cmp_gt_i32 s6, 0
	v_mov_b32_e32 v73, 0xf149f2ca
	v_mov_b32_e32 v75, 0xf149f2ca
	v_mov_b32_e32 v132, 0xf149f2ca
	v_mov_b32_e32 v59, 0xf149f2ca
	v_mov_b32_e32 v1, 0xf149f2ca
	v_or_b32_e32 v184, s69, v103
	v_mul_u32_u24_e32 v184, 0x90, v184
	v_add_u32_e32 v184, v184, v66
	ds_read_b128 v[192:195], v184
	ds_read_b128 v[196:199], v184 offset:64
	ds_read_b128 v[200:203], v184 offset:2304
	ds_read_b128 v[204:207], v184 offset:2368
	ds_read_b128 v[208:211], v184 offset:4608
	ds_read_b128 v[212:215], v184 offset:4672
	ds_read_b128 v[216:219], v184 offset:6912
	ds_read_b128 v[220:223], v184 offset:6976
	ds_read_b128 v[224:227], v184 offset:9216
	ds_read_b128 v[228:231], v184 offset:9280
	ds_read_b128 v[162:165], v184 offset:11520
	ds_read_b128 v[166:169], v184 offset:11584
	ds_read_b128 v[170:173], v184 offset:13824
	ds_read_b128 v[180:183], v184 offset:13888
	s_cbranch_scc1 .LBB0_235
	v_or_b32_e32 v1, s69, v103
	v_mad_u64_u32 v[54:55], s[26:27], v1, s73, v[66:67]
	v_mul_f32_e32 v54, 0, v58
	s_mov_b32 s7, 0xf149f2ca
	s_waitcnt lgkmcnt(13)
	v_mfma_f32_16x16x32_bf16 v[76:79], v[192:195], v[48:51], 0
	s_waitcnt lgkmcnt(12)
	v_mfma_f32_16x16x32_bf16 v[76:79], v[196:199], v[44:47], v[76:79]
	v_add_f32_e64 v80, v56, v54
	v_add_f32_e64 v81, v57, v54
	v_pk_add_f32 v[54:55], v[52:53], v[54:55] op_sel_hi:[1,0]
	s_nop 4
	v_pk_fma_f32 v[76:77], v[76:77], s[72:73], v[80:81] op_sel_hi:[1,0,1]
	v_pk_fma_f32 v[54:55], v[78:79], s[72:73], v[54:55] op_sel_hi:[1,0,1]
	v_cndmask_b32_e64 v59, v76, v178, s[38:39]
	v_cndmask_b32_e64 v1, v77, v178, s[36:37]
	v_max3_f32 v3, v59, s7, v1
	v_cndmask_b32_e64 v75, v54, v178, s[42:43]
	v_cndmask_b32_e64 v132, v55, v178, s[40:41]
	v_max3_f32 v73, v3, v75, v132
.LBB0_235:
	ds_read_b128 v[192:195], v184 offset:16128
	ds_read_b128 v[196:199], v184 offset:16192
	s_cmp_lt_i32 s6, 2
	s_cselect_b64 s[56:57], -1, 0
	s_cmp_gt_i32 s6, 1
	s_cbranch_scc1 .LBB0_237
	v_add_u32_e32 v2, s69, v106
	v_mad_u64_u32 v[2:3], s[26:27], v2, s73, v[66:67]
	v_pk_add_f32 v[2:3], v[58:59], v[56:57] op_sel_hi:[0,1]
	v_pk_add_f32 v[54:55], v[58:59], v[52:53] op_sel_hi:[0,1]
	s_waitcnt lgkmcnt(13)
	v_mfma_f32_16x16x32_bf16 v[76:79], v[200:203], v[48:51], 0
	s_waitcnt lgkmcnt(12)
	v_mfma_f32_16x16x32_bf16 v[76:79], v[204:207], v[44:47], v[76:79]
	s_nop 7
	v_pk_fma_f32 v[76:77], v[76:77], s[72:73], v[2:3] op_sel_hi:[1,0,1]
	v_pk_fma_f32 v[2:3], v[78:79], s[72:73], v[54:55] op_sel_hi:[1,0,1]
	v_max3_f32 v73, v73, v76, v77
	v_max3_f32 v73, v73, v2, v3
	s_branch .LBB0_238

; #define LAS __attribute__((address_space(3)))
; __device__ __forceinline__ void attn_compute(const MixCtx& X, int a, LAS unsigned char* lds, int tid, const bf16x8 q0, const bf16x8 q1) {
;     ...
;     for (int tt = 0; tt < 9; ++tt) {
;         if (tt >= nlive0) {
;             const int kt = w + tt; const LAS unsigned char* p = Kl + (16 * kt + j) * 144 + kq * 16;
;             const bf16x8 k0f = *(const LAS bf16x8*)p, k1f = *(const LAS bf16x8*)(p + 64);
;             f32x4 acc = (f32x4){0.f, 0.f, 0.f, 0.f};
;             acc = __builtin_amdgcn_mfma_f32_16x16x32_bf16(k0f, q0, acc, 0, 0, 0);
;             acc = __builtin_amdgcn_mfma_f32_16x16x32_bf16(k1f, q1, acc, 0, 0, 0);
; #pragma unroll
;             for (int e = 0; e < 4; ++e) {
;                 float v = acc[e] * c1 + (be[e] + bstep * (float)tt);
;                 if (tt == 0) { if (d0 - e > 128) v = -1e30f; }
;                 if (tt == 8) { if (d0 - 128 - e < 0) v = -1e30f; }
;                 s[tt][e] = v; mx = fmaxf(mx, v); }
.LBB0_238:
	ds_read_b128 v[200:203], v184 offset:18432
	ds_read_b128 v[204:207], v184 offset:18496
	s_cmp_lt_i32 s6, 3
	s_cselect_b64 s[58:59], -1, 0
	s_cmp_gt_i32 s6, 2
	v_mov_b32_e32 v54, 0xf149f2ca
	s_cbranch_scc1 .LBB0_241
	v_add_u32_e32 v55, s69, v107
	v_mad_u64_u32 v[82:83], s[26:27], v55, s73, v[66:67]
	s_waitcnt lgkmcnt(13)
	v_mfma_f32_16x16x32_bf16 v[78:81], v[208:211], v[48:51], 0
	s_waitcnt lgkmcnt(12)
	v_mfma_f32_16x16x32_bf16 v[78:81], v[212:215], v[44:47], v[78:81]
	v_add_f32_e32 v82, v58, v58
	v_pk_add_f32 v[84:85], v[56:57], v[82:83] op_sel_hi:[1,0]
	v_pk_add_f32 v[82:83], v[52:53], v[82:83] op_sel_hi:[1,0]
	s_nop 4
	v_pk_fma_f32 v[78:79], v[78:79], s[72:73], v[84:85] op_sel_hi:[1,0,1]
	v_pk_fma_f32 v[80:81], v[80:81], s[72:73], v[82:83] op_sel_hi:[1,0,1]
	v_max3_f32 v55, v73, v78, v79
	v_max3_f32 v73, v55, v80, v81
	s_cmp_lt_i32 s6, 4
	s_cselect_b64 s[26:27], -1, 0
	s_cmp_gt_i32 s6, 3
	s_cbranch_scc0 .LBB0_242

; #define LAS __attribute__((address_space(3)))
; __device__ __forceinline__ void attn_compute(const MixCtx& X, int a, LAS unsigned char* lds, int tid, const bf16x8 q0, const bf16x8 q1) {
;     ...
;     for (int tt = 0; tt < 9; ++tt) {
;         if (tt >= nlive0) {
;             const int kt = w + tt; const LAS unsigned char* p = Kl + (16 * kt + j) * 144 + kq * 16;
;             const bf16x8 k0f = *(const LAS bf16x8*)p, k1f = *(const LAS bf16x8*)(p + 64);
;             f32x4 acc = (f32x4){0.f, 0.f, 0.f, 0.f};
;             acc = __builtin_amdgcn_mfma_f32_16x16x32_bf16(k0f, q0, acc, 0, 0, 0);
;             acc = __builtin_amdgcn_mfma_f32_16x16x32_bf16(k1f, q1, acc, 0, 0, 0);
; #pragma unroll
;             for (int e = 0; e < 4; ++e) {
;                 float v = acc[e] * c1 + (be[e] + bstep * (float)tt);
;                 if (tt == 0) { if (d0 - e > 128) v = -1e30f; }
;                 if (tt == 8) { if (d0 - 128 - e < 0) v = -1e30f; }
;                 s[tt][e] = v; mx = fmaxf(mx, v); }
.LBB0_242:
	v_add_u32_e32 v54, s69, v108
	v_mad_u64_u32 v[54:55], s[60:61], v54, s73, v[66:67]
	v_mul_f32_e32 v54, 0x40400000, v58
	s_waitcnt lgkmcnt(11)
	v_mfma_f32_16x16x32_bf16 v[82:85], v[216:219], v[48:51], 0
	s_waitcnt lgkmcnt(10)
	v_mfma_f32_16x16x32_bf16 v[82:85], v[220:223], v[44:47], v[82:85]
	v_add_f32_e64 v86, v56, v54
	v_add_f32_e64 v87, v57, v54
	v_pk_add_f32 v[54:55], v[52:53], v[54:55] op_sel_hi:[1,0]
	s_nop 4
	v_pk_fma_f32 v[82:83], v[82:83], s[72:73], v[86:87] op_sel_hi:[1,0,1]
	v_pk_fma_f32 v[54:55], v[84:85], s[72:73], v[54:55] op_sel_hi:[1,0,1]
	v_max3_f32 v73, v73, v82, v83
	v_max3_f32 v73, v73, v54, v55
.LBB0_243:
	s_cmp_lt_i32 s6, 5
	s_cselect_b64 s[78:79], -1, 0
	s_cmp_gt_i32 s6, 4
	v_mov_b32_e32 v84, 0xf149f2ca
	s_cbranch_scc1 .LBB0_246
	v_add_u32_e32 v85, s69, v109
	v_mad_u64_u32 v[90:91], s[60:61], v85, s73, v[66:67]
	s_waitcnt lgkmcnt(9)
	v_mfma_f32_16x16x32_bf16 v[86:89], v[224:227], v[48:51], 0
	s_waitcnt lgkmcnt(8)
	v_mfma_f32_16x16x32_bf16 v[86:89], v[228:231], v[44:47], v[86:89]
	v_mul_f32_e32 v90, 4.0, v58
	v_pk_add_f32 v[92:93], v[56:57], v[90:91] op_sel_hi:[1,0]
	v_pk_add_f32 v[90:91], v[52:53], v[90:91] op_sel_hi:[1,0]
	s_nop 4
	v_pk_fma_f32 v[86:87], v[86:87], s[72:73], v[92:93] op_sel_hi:[1,0,1]
	v_pk_fma_f32 v[88:89], v[88:89], s[72:73], v[90:91] op_sel_hi:[1,0,1]
	v_max3_f32 v73, v73, v86, v87
	v_max3_f32 v73, v73, v88, v89
	s_cmp_lt_i32 s6, 6
	s_cselect_b64 s[82:83], -1, 0
	s_cmp_gt_i32 s6, 5
	s_cbranch_scc0 .LBB0_247

; #define LAS __attribute__((address_space(3)))
; __device__ __forceinline__ void attn_compute(const MixCtx& X, int a, LAS unsigned char* lds, int tid, const bf16x8 q0, const bf16x8 q1) {
;     ...
;     for (int tt = 0; tt < 9; ++tt) {
;         if (tt >= nlive0) {
;             const int kt = w + tt; const LAS unsigned char* p = Kl + (16 * kt + j) * 144 + kq * 16;
;             const bf16x8 k0f = *(const LAS bf16x8*)p, k1f = *(const LAS bf16x8*)(p + 64);
;             f32x4 acc = (f32x4){0.f, 0.f, 0.f, 0.f};
;             acc = __builtin_amdgcn_mfma_f32_16x16x32_bf16(k0f, q0, acc, 0, 0, 0);
;             acc = __builtin_amdgcn_mfma_f32_16x16x32_bf16(k1f, q1, acc, 0, 0, 0);
; #pragma unroll
;             for (int e = 0; e < 4; ++e) {
;                 float v = acc[e] * c1 + (be[e] + bstep * (float)tt);
;                 if (tt == 0) { if (d0 - e > 128) v = -1e30f; }
;                 if (tt == 8) { if (d0 - 128 - e < 0) v = -1e30f; }
;                 s[tt][e] = v; mx = fmaxf(mx, v); }
.LBB0_247:
	v_add_u32_e32 v84, s69, v110
	v_mad_u64_u32 v[84:85], s[60:61], v84, s73, v[66:67]
	v_mul_f32_e32 v84, 0x40a00000, v58
	s_waitcnt lgkmcnt(7)
	v_mfma_f32_16x16x32_bf16 v[90:93], v[162:165], v[48:51], 0
	s_waitcnt lgkmcnt(6)
	v_mfma_f32_16x16x32_bf16 v[90:93], v[166:169], v[44:47], v[90:93]
	v_add_f32_e64 v94, v56, v84
	v_add_f32_e64 v95, v57, v84
	v_pk_add_f32 v[84:85], v[52:53], v[84:85] op_sel_hi:[1,0]
	s_nop 4
	v_pk_fma_f32 v[90:91], v[90:91], s[72:73], v[94:95] op_sel_hi:[1,0,1]
	v_pk_fma_f32 v[84:85], v[92:93], s[72:73], v[84:85] op_sel_hi:[1,0,1]
	v_max3_f32 v73, v73, v90, v91
	v_max3_f32 v73, v73, v84, v85
.LBB0_248:
	s_cmp_lt_i32 s6, 7
	s_cselect_b64 s[76:77], -1, 0
	s_cmp_gt_i32 s6, 6
	v_mov_b32_e32 v92, 0xf149f2ca
	s_cbranch_scc1 .LBB0_251
	v_add_u32_e32 v93, s69, v111
	v_mad_u64_u32 v[98:99], s[60:61], v93, s73, v[66:67]
	v_mul_f32_e32 v98, 0x40c00000, v58
	s_waitcnt lgkmcnt(5)
	v_mfma_f32_16x16x32_bf16 v[94:97], v[170:173], v[48:51], 0
	s_waitcnt lgkmcnt(4)
	v_mfma_f32_16x16x32_bf16 v[94:97], v[180:183], v[44:47], v[94:97]
	v_add_f32_e64 v134, v56, v98
	v_add_f32_e64 v135, v57, v98
	v_pk_add_f32 v[98:99], v[52:53], v[98:99] op_sel_hi:[1,0]
	s_nop 4
	v_pk_fma_f32 v[94:95], v[94:95], s[72:73], v[134:135] op_sel_hi:[1,0,1]
	v_pk_fma_f32 v[96:97], v[96:97], s[72:73], v[98:99] op_sel_hi:[1,0,1]
	v_max3_f32 v73, v73, v94, v95
	v_max3_f32 v73, v73, v96, v97
	s_cmp_lt_i32 s6, 8
	s_cselect_b64 s[80:81], -1, 0
	s_cmp_gt_i32 s6, 7
	s_cbranch_scc0 .LBB0_252

; #define LAS __attribute__((address_space(3)))
; __device__ __forceinline__ void attn_compute(const MixCtx& X, int a, LAS unsigned char* lds, int tid, const bf16x8 q0, const bf16x8 q1) {
;     ...
;     for (int tt = 0; tt < 9; ++tt) {
;         if (tt >= nlive0) {
;             const int kt = w + tt; const LAS unsigned char* p = Kl + (16 * kt + j) * 144 + kq * 16;
;             const bf16x8 k0f = *(const LAS bf16x8*)p, k1f = *(const LAS bf16x8*)(p + 64);
;             f32x4 acc = (f32x4){0.f, 0.f, 0.f, 0.f};
;             acc = __builtin_amdgcn_mfma_f32_16x16x32_bf16(k0f, q0, acc, 0, 0, 0);
;             acc = __builtin_amdgcn_mfma_f32_16x16x32_bf16(k1f, q1, acc, 0, 0, 0);
; #pragma unroll
;             for (int e = 0; e < 4; ++e) {
;                 float v = acc[e] * c1 + (be[e] + bstep * (float)tt);
;                 if (tt == 0) { if (d0 - e > 128) v = -1e30f; }
;                 if (tt == 8) { if (d0 - 128 - e < 0) v = -1e30f; }
;                 s[tt][e] = v; mx = fmaxf(mx, v); }
.LBB0_252:
	v_add_u32_e32 v92, s69, v112
	v_mad_u64_u32 v[92:93], s[60:61], v92, s73, v[66:67]
	v_mul_f32_e32 v92, 0x40e00000, v58
	v_pk_add_f32 v[98:99], v[56:57], v[92:93] op_sel_hi:[1,0]
	s_waitcnt lgkmcnt(3)
	v_mfma_f32_16x16x32_bf16 v[134:137], v[192:195], v[48:51], 0
	v_pk_add_f32 v[92:93], v[52:53], v[92:93] op_sel_hi:[1,0]
	s_waitcnt lgkmcnt(2)
	v_mfma_f32_16x16x32_bf16 v[134:137], v[196:199], v[44:47], v[134:137]
	s_nop 7
	v_pk_fma_f32 v[98:99], v[134:135], s[72:73], v[98:99] op_sel_hi:[1,0,1]
	v_pk_fma_f32 v[92:93], v[136:137], s[72:73], v[92:93] op_sel_hi:[1,0,1]
	v_max3_f32 v73, v73, v98, v99
	v_max3_f32 v73, v73, v92, v93
.LBB0_253:
	s_cmp_lt_i32 s6, 9
	s_cselect_b64 s[84:85], -1, 0
	s_cmp_gt_i32 s6, 8
	v_mov_b32_e32 v134, 0xf149f2ca
	s_cbranch_scc1 .LBB0_255
	v_add_u32_e32 v133, s69, v105
	v_mad_u64_u32 v[148:149], s[60:61], v133, s73, v[66:67]
	v_mul_f32_e32 v58, 0x41000000, v58
	v_pk_add_f32 v[56:57], v[56:57], v[58:59] op_sel_hi:[1,0]
	s_waitcnt lgkmcnt(1)
	v_mfma_f32_16x16x32_bf16 v[48:51], v[200:203], v[48:51], 0
	v_add_f32_e64 v52, v52, v58
	v_add_f32_e64 v53, v53, v58
	s_waitcnt lgkmcnt(0)
	v_mfma_f32_16x16x32_bf16 v[44:47], v[204:207], v[44:47], v[48:51]
	s_nop 7
	v_pk_fma_f32 v[44:45], v[44:45], s[72:73], v[56:57] op_sel_hi:[1,0,1]
	v_pk_fma_f32 v[48:49], v[46:47], s[72:73], v[52:53] op_sel_hi:[1,0,1]
	v_cndmask_b32_e64 v134, v44, v178, s[46:47]
	v_cndmask_b32_e64 v47, v45, v178, s[44:45]
	v_cndmask_b32_e64 v45, v48, v178, s[50:51]
	v_max3_f32 v44, v73, v134, v47
	v_cndmask_b32_e64 v46, v49, v178, s[48:49]
	v_max3_f32 v73, v44, v45, v46
	s_branch .LBB0_256
